# GEMM0 K-loop: first iteration peeled with SrcC=0, per-tile 128-mov accumulator zeroing removed
# speedup vs baseline: 1.0075x; 1.0024x over previous
; #define PG8_STAGE(bufoff, gbase, voff) do { _Pragma("unroll") for (int _i = 0; _i < 2; ++_i) \
;         __builtin_amdgcn_global_load_lds((const unsigned*)((const char*)(gbase) + (voff)[_i]), (PG8_LAS unsigned*)(lds + (bufoff) + ldsw + _i * 8192), 16, 0, 0); } while (0)
; #define PG8_LDA(dst, b, h) do { _Pragma("unroll") for (int m = 0; m < 4; ++m) _Pragma("unroll") for (int k = 0; k < 2; ++k) dst[m][k] = *(const PG8_LAS bf16x8*)(lds + PG8_SA(b, h) + aoff + m * 2048 + k * 1024); } while (0)
; #define PG8_LDB(dst, b, h) do { _Pragma("unroll") for (int n = 0; n < 2; ++n) _Pragma("unroll") for (int k = 0; k < 2; ++k) dst[n][k] = *(const PG8_LAS bf16x8*)(lds + PG8_SB(b, h) + boff + n * 2048 + k * 1024); } while (0)
; #define PG8_MMA(ai, bj, At, Bt) do { __builtin_amdgcn_s_setprio(1); _Pragma("unroll") for (int m = 0; m < 4; ++m) _Pragma("unroll") for (int n = 0; n < 2; ++n) _Pragma("unroll") for (int k = 0; k < 2; ++k) \
;         acc[ai][bj][m][n] = __builtin_amdgcn_mfma_f32_16x16x32_bf16(Bt[n][k], At[m][k], acc[ai][bj][m][n], 0, 0, 0); __builtin_amdgcn_s_setprio(0); } while (0)
; #define PG8_WAIT_V(n) asm volatile("s_waitcnt vmcnt(" #n ")" ::: "memory")
; #define PG8_WAIT_L(n) asm volatile("s_waitcnt lgkmcnt(" #n ")" ::: "memory")
; #define PG8_BAR __builtin_amdgcn_s_barrier()
; #define PG8_SCHED __builtin_amdgcn_sched_barrier(0)
; template <class Epi, class Sched>
; __device__ __forceinline__ void gemm_phase(PG8_LAS unsigned char* lds, const Gemm g, const Sched& S, const Epi& E) {
;     ...
;         for (int t = 0; t < nt; t += 2) {
;             const bool last = (t == nt - 2);
;             const char* a1 = cA + (size_t)(t + 1) * kstep;
;             const char* a2 = last ? nA : cA + (size_t)(t + 2) * kstep; const char* b2 = last ? nB : cB + (size_t)(t + 2) * kstep;
;             const char* a3 = a2 + kstep; const char* b3 = b2 + kstep;
;             PG8_LDB(B0, 0, 0); PG8_LDB(B1, 0, 1); PG8_SCHED; PG8_LDA(At, 0, 0); PG8_STAGE(PG8_SA(1, 1), a1 + hstep, voffA);
;             PG8_WAIT_V(8); PG8_WAIT_L(0); PG8_BAR; PG8_MMA(0, 0, At, B0); PG8_MMA(0, 1, At, B1); PG8_BAR; PG8_SCHED;
;             PG8_LDA(At, 0, 1); PG8_STAGE(PG8_SB(0, 0), b2, voffB); PG8_STAGE(PG8_SB(0, 1), b2 + hstep, voffB); PG8_STAGE(PG8_SA(0, 0), a2, voffA);
;             PG8_WAIT_V(8); PG8_WAIT_L(0); PG8_BAR; PG8_MMA(1, 0, At, B0); PG8_MMA(1, 1, At, B1); PG8_BAR; PG8_SCHED;
.LBB0_317:
	s_add_u32 s42, s42, 0x80
	s_addc_u32 s43, s43, 0
	s_add_u32 s14, s46, 0x100
	s_addc_u32 s15, s47, 0
	s_mov_b32 s34, 0
	s_add_i32 s55, s34, 2
	s_add_u32 s46, s42, 0x80
	s_addc_u32 s47, s43, 0
	s_add_i32 s58, 0, 0x10000
	s_cmp_eq_u32 s39, s34
	s_cselect_b32 s47, s27, s47
	s_cselect_b32 s46, s26, s46
	v_add_u32_e32 v154, s58, v157
	s_cselect_b32 s57, s45, s15
	s_cselect_b32 s56, s44, s14
	s_add_i32 s34, 0, 0x14000
	ds_read_b128 v[130:133], v154
	ds_read_b128 v[146:149], v154 offset:1024
	ds_read_b128 v[150:153], v154 offset:2048
	ds_read_b128 v[160:163], v154 offset:3072
	v_add_u32_e32 v154, s34, v157
	ds_read_b128 v[164:167], v154
	ds_read_b128 v[168:171], v154 offset:1024
	ds_read_b128 v[172:175], v154 offset:2048
	ds_read_b128 v[176:179], v154 offset:3072
	v_lshl_add_u64 v[154:155], s[42:43], 0, v[142:143]
	s_add_i32 m0, s4, 0xc000
	ds_read_b128 v[180:183], v158
	ds_read_b128 v[184:187], v158 offset:1024
	ds_read_b128 v[188:191], v158 offset:2048
	ds_read_b128 v[192:195], v158 offset:3072
	ds_read_b128 v[202:205], v158 offset:4096
	ds_read_b128 v[206:209], v158 offset:5120
	ds_read_b128 v[210:213], v158 offset:6144
	ds_read_b128 v[214:217], v158 offset:7168
	global_load_lds_dwordx4 v[154:155], off
	v_lshl_add_u64 v[154:155], s[42:43], 0, v[144:145]
	s_add_i32 m0, s4, 0xe000
	s_nop 0
	global_load_lds_dwordx4 v[154:155], off
	s_waitcnt vmcnt(8)
	s_waitcnt lgkmcnt(0)
	s_barrier
	s_setprio 1
	s_waitcnt lgkmcnt(0)
	v_mfma_f32_16x16x32_bf16 v[126:129], v[130:133], v[180:183], 0
	v_mfma_f32_16x16x32_bf16 v[118:121], v[150:153], v[180:183], 0
	v_mfma_f32_16x16x32_bf16 v[110:113], v[130:133], v[188:191], 0
	v_mfma_f32_16x16x32_bf16 v[102:105], v[150:153], v[188:191], 0
	v_mfma_f32_16x16x32_bf16 v[94:97], v[130:133], v[202:205], 0
	v_mfma_f32_16x16x32_bf16 v[86:89], v[150:153], v[202:205], 0
	v_mfma_f32_16x16x32_bf16 v[78:81], v[130:133], v[210:213], 0
	v_mfma_f32_16x16x32_bf16 v[70:73], v[150:153], v[210:213], 0
	v_mfma_f32_16x16x32_bf16 v[126:129], v[146:149], v[184:187], v[126:129]
	v_mfma_f32_16x16x32_bf16 v[118:121], v[160:163], v[184:187], v[118:121]
	v_mfma_f32_16x16x32_bf16 v[110:113], v[146:149], v[192:195], v[110:113]
	v_mfma_f32_16x16x32_bf16 v[102:105], v[160:163], v[192:195], v[102:105]
	v_mfma_f32_16x16x32_bf16 v[94:97], v[146:149], v[206:209], v[94:97]
	v_mfma_f32_16x16x32_bf16 v[86:89], v[160:163], v[206:209], v[86:89]
	v_mfma_f32_16x16x32_bf16 v[78:81], v[146:149], v[214:217], v[78:81]
	v_mfma_f32_16x16x32_bf16 v[70:73], v[160:163], v[214:217], v[70:73]
	s_setprio 0
	s_setprio 1
	v_mfma_f32_16x16x32_bf16 v[122:125], v[164:167], v[180:183], 0
	v_mfma_f32_16x16x32_bf16 v[114:117], v[172:175], v[180:183], 0
	v_mfma_f32_16x16x32_bf16 v[106:109], v[164:167], v[188:191], 0
	v_mfma_f32_16x16x32_bf16 v[98:101], v[172:175], v[188:191], 0
	v_mfma_f32_16x16x32_bf16 v[90:93], v[164:167], v[202:205], 0
	v_mfma_f32_16x16x32_bf16 v[82:85], v[172:175], v[202:205], 0
	v_mfma_f32_16x16x32_bf16 v[74:77], v[164:167], v[210:213], 0
	v_mfma_f32_16x16x32_bf16 v[66:69], v[172:175], v[210:213], 0
	v_mfma_f32_16x16x32_bf16 v[122:125], v[168:171], v[184:187], v[122:125]
	v_mfma_f32_16x16x32_bf16 v[114:117], v[176:179], v[184:187], v[114:117]
	v_mfma_f32_16x16x32_bf16 v[106:109], v[168:171], v[192:195], v[106:109]
	v_mfma_f32_16x16x32_bf16 v[98:101], v[176:179], v[192:195], v[98:101]
	v_mfma_f32_16x16x32_bf16 v[90:93], v[168:171], v[206:209], v[90:93]
	v_mfma_f32_16x16x32_bf16 v[82:85], v[176:179], v[206:209], v[82:85]
	v_mfma_f32_16x16x32_bf16 v[74:77], v[168:171], v[214:217], v[74:77]
	v_mfma_f32_16x16x32_bf16 v[66:69], v[176:179], v[214:217], v[66:69]
	s_setprio 0
	s_barrier
	s_add_i32 s58, s58, s3
	v_lshl_add_u64 v[154:155], s[56:57], 0, v[136:137]
	s_mov_b32 m0, s58
	ds_read_b128 v[180:183], v158 offset:16384
	ds_read_b128 v[184:187], v158 offset:17408
	ds_read_b128 v[188:191], v158 offset:18432
	ds_read_b128 v[192:195], v158 offset:19456
	ds_read_b128 v[202:205], v158 offset:20480
	ds_read_b128 v[206:209], v158 offset:21504
	ds_read_b128 v[210:213], v158 offset:22528
	ds_read_b128 v[214:217], v158 offset:23552
	global_load_lds_dwordx4 v[154:155], off
	s_add_i32 m0, s58, 0x2000
	v_lshl_add_u64 v[196:197], s[56:57], 0, v[140:141]
	s_add_u32 s56, s56, s70
	s_addc_u32 s57, s57, 0
	s_add_i32 s34, s34, s3
	global_load_lds_dwordx4 v[196:197], off
	v_lshl_add_u64 v[218:219], s[56:57], 0, v[136:137]
	s_mov_b32 m0, s34
	v_lshl_add_u64 v[220:221], s[56:57], 0, v[140:141]
	global_load_lds_dwordx4 v[218:219], off
	s_add_i32 m0, s34, 0x2000
	v_lshl_add_u64 v[222:223], s[46:47], 0, v[134:135]
	global_load_lds_dwordx4 v[220:221], off
	s_mov_b32 m0, s4
	v_lshl_add_u64 v[224:225], s[46:47], 0, v[138:139]
	global_load_lds_dwordx4 v[222:223], off
	s_mov_b32 m0, s19
	s_nop 0
	global_load_lds_dwordx4 v[224:225], off
	s_waitcnt vmcnt(8)
	s_waitcnt lgkmcnt(0)
	s_barrier
; #define PG8_STAGE(bufoff, gbase, voff) do { _Pragma("unroll") for (int _i = 0; _i < 2; ++_i) \
;         __builtin_amdgcn_global_load_lds((const unsigned*)((const char*)(gbase) + (voff)[_i]), (PG8_LAS unsigned*)(lds + (bufoff) + ldsw + _i * 8192), 16, 0, 0); } while (0)
; #define PG8_LDA(dst, b, h) do { _Pragma("unroll") for (int m = 0; m < 4; ++m) _Pragma("unroll") for (int k = 0; k < 2; ++k) dst[m][k] = *(const PG8_LAS bf16x8*)(lds + PG8_SA(b, h) + aoff + m * 2048 + k * 1024); } while (0)
; #define PG8_LDB(dst, b, h) do { _Pragma("unroll") for (int n = 0; n < 2; ++n) _Pragma("unroll") for (int k = 0; k < 2; ++k) dst[n][k] = *(const PG8_LAS bf16x8*)(lds + PG8_SB(b, h) + boff + n * 2048 + k * 1024); } while (0)
; #define PG8_MMA(ai, bj, At, Bt) do { __builtin_amdgcn_s_setprio(1); _Pragma("unroll") for (int m = 0; m < 4; ++m) _Pragma("unroll") for (int n = 0; n < 2; ++n) _Pragma("unroll") for (int k = 0; k < 2; ++k) \
;         acc[ai][bj][m][n] = __builtin_amdgcn_mfma_f32_16x16x32_bf16(Bt[n][k], At[m][k], acc[ai][bj][m][n], 0, 0, 0); __builtin_amdgcn_s_setprio(0); } while (0)
; #define PG8_WAIT_V(n) asm volatile("s_waitcnt vmcnt(" #n ")" ::: "memory")
; #define PG8_WAIT_L(n) asm volatile("s_waitcnt lgkmcnt(" #n ")" ::: "memory")
; #define PG8_BAR __builtin_amdgcn_s_barrier()
; #define PG8_SCHED __builtin_amdgcn_sched_barrier(0)
; template <class Epi, class Sched>
; __device__ __forceinline__ void gemm_phase(PG8_LAS unsigned char* lds, const Gemm g, const Sched& S, const Epi& E) {
;     ...
;             PG8_WAIT_V(8); PG8_WAIT_L(0); PG8_BAR; PG8_MMA(1, 0, At, B0); PG8_MMA(1, 1, At, B1); PG8_BAR; PG8_SCHED;
;             PG8_LDB(B0, 1, 0); PG8_LDB(B1, 1, 1); PG8_SCHED; PG8_LDA(At, 1, 0); PG8_STAGE(PG8_SA(0, 1), a2 + hstep, voffA);
;             PG8_WAIT_V(8); PG8_WAIT_L(0); PG8_BAR; PG8_MMA(0, 0, At, B0); PG8_MMA(0, 1, At, B1); PG8_BAR; PG8_SCHED;
;             PG8_LDA(At, 1, 1); PG8_STAGE(PG8_SB(1, 0), b3, voffB); PG8_STAGE(PG8_SB(1, 1), b3 + hstep, voffB); PG8_STAGE(PG8_SA(1, 0), a3, voffA);
;             PG8_WAIT_V(8); PG8_WAIT_L(0); PG8_BAR; PG8_MMA(1, 0, At, B0); PG8_MMA(1, 1, At, B1); PG8_BAR; PG8_SCHED;
	s_setprio 1
	s_waitcnt lgkmcnt(0)
	v_mfma_f32_16x16x32_bf16 v[62:65], v[130:133], v[180:183], 0
	v_mfma_f32_16x16x32_bf16 v[54:57], v[150:153], v[180:183], 0
	v_mfma_f32_16x16x32_bf16 v[46:49], v[130:133], v[188:191], 0
	v_mfma_f32_16x16x32_bf16 v[38:41], v[150:153], v[188:191], 0
	v_mfma_f32_16x16x32_bf16 v[30:33], v[130:133], v[202:205], 0
	v_mfma_f32_16x16x32_bf16 v[22:25], v[150:153], v[202:205], 0
	v_mfma_f32_16x16x32_bf16 v[14:17], v[130:133], v[210:213], 0
	v_mfma_f32_16x16x32_bf16 v[6:9], v[150:153], v[210:213], 0
	v_mfma_f32_16x16x32_bf16 v[62:65], v[146:149], v[184:187], v[62:65]
	v_mfma_f32_16x16x32_bf16 v[54:57], v[160:163], v[184:187], v[54:57]
	v_mfma_f32_16x16x32_bf16 v[46:49], v[146:149], v[192:195], v[46:49]
	v_mfma_f32_16x16x32_bf16 v[38:41], v[160:163], v[192:195], v[38:41]
	v_mfma_f32_16x16x32_bf16 v[30:33], v[146:149], v[206:209], v[30:33]
	v_mfma_f32_16x16x32_bf16 v[22:25], v[160:163], v[206:209], v[22:25]
	v_mfma_f32_16x16x32_bf16 v[14:17], v[146:149], v[214:217], v[14:17]
	v_mfma_f32_16x16x32_bf16 v[6:9], v[160:163], v[214:217], v[6:9]
	s_setprio 0
	s_setprio 1
	v_mfma_f32_16x16x32_bf16 v[58:61], v[164:167], v[180:183], 0
	v_mfma_f32_16x16x32_bf16 v[50:53], v[172:175], v[180:183], 0
	v_mfma_f32_16x16x32_bf16 v[42:45], v[164:167], v[188:191], 0
	v_mfma_f32_16x16x32_bf16 v[34:37], v[172:175], v[188:191], 0
	v_mfma_f32_16x16x32_bf16 v[26:29], v[164:167], v[202:205], 0
	v_mfma_f32_16x16x32_bf16 v[18:21], v[172:175], v[202:205], 0
	v_mfma_f32_16x16x32_bf16 v[10:13], v[164:167], v[210:213], 0
	v_mfma_f32_16x16x32_bf16 v[2:5], v[172:175], v[210:213], 0
	v_mfma_f32_16x16x32_bf16 v[58:61], v[168:171], v[184:187], v[58:61]
	v_mfma_f32_16x16x32_bf16 v[50:53], v[176:179], v[184:187], v[50:53]
	v_mfma_f32_16x16x32_bf16 v[42:45], v[168:171], v[192:195], v[42:45]
	v_mfma_f32_16x16x32_bf16 v[34:37], v[176:179], v[192:195], v[34:37]
	v_mfma_f32_16x16x32_bf16 v[26:29], v[168:171], v[206:209], v[26:29]
	v_mfma_f32_16x16x32_bf16 v[18:21], v[176:179], v[206:209], v[18:21]
	v_mfma_f32_16x16x32_bf16 v[10:13], v[168:171], v[214:217], v[10:13]
	v_mfma_f32_16x16x32_bf16 v[2:5], v[176:179], v[214:217], v[2:5]
	s_setprio 0
	s_barrier
	s_add_i32 s34, 0, 0x18000
	v_add_u32_e32 v159, s34, v157
	s_add_i32 s56, 0, 0x1c000
	ds_read_b128 v[130:133], v159
	ds_read_b128 v[146:149], v159 offset:1024
	ds_read_b128 v[150:153], v159 offset:2048
	ds_read_b128 v[160:163], v159 offset:3072
	v_add_u32_e32 v159, s56, v157
	ds_read_b128 v[164:167], v159
	ds_read_b128 v[168:171], v159 offset:1024
	ds_read_b128 v[172:175], v159 offset:2048
	ds_read_b128 v[176:179], v159 offset:3072
	s_add_u32 s46, s46, s70
	s_addc_u32 s47, s47, 0
	s_mov_b32 m0, s22
	v_lshl_add_u64 v[226:227], s[46:47], 0, v[134:135]
	ds_read_b128 v[180:183], v158 offset:32768
	ds_read_b128 v[184:187], v158 offset:33792
	ds_read_b128 v[188:191], v158 offset:34816
	ds_read_b128 v[192:195], v158 offset:35840
	ds_read_b128 v[202:205], v158 offset:36864
	ds_read_b128 v[206:209], v158 offset:37888
	ds_read_b128 v[210:213], v158 offset:38912
	ds_read_b128 v[214:217], v158 offset:39936
	global_load_lds_dwordx4 v[226:227], off
	v_lshl_add_u64 v[226:227], s[46:47], 0, v[138:139]
	s_mov_b32 m0, s24
	s_nop 0
	global_load_lds_dwordx4 v[226:227], off
	s_waitcnt vmcnt(8)
	s_waitcnt lgkmcnt(0)
	s_barrier
	s_setprio 1
	s_waitcnt lgkmcnt(0)
	v_mfma_f32_16x16x32_bf16 v[126:129], v[130:133], v[180:183], v[126:129]
	v_mfma_f32_16x16x32_bf16 v[118:121], v[150:153], v[180:183], v[118:121]
	v_mfma_f32_16x16x32_bf16 v[110:113], v[130:133], v[188:191], v[110:113]
	v_mfma_f32_16x16x32_bf16 v[102:105], v[150:153], v[188:191], v[102:105]
	v_mfma_f32_16x16x32_bf16 v[94:97], v[130:133], v[202:205], v[94:97]
	v_mfma_f32_16x16x32_bf16 v[86:89], v[150:153], v[202:205], v[86:89]
	v_mfma_f32_16x16x32_bf16 v[78:81], v[130:133], v[210:213], v[78:81]
	v_mfma_f32_16x16x32_bf16 v[70:73], v[150:153], v[210:213], v[70:73]
	v_mfma_f32_16x16x32_bf16 v[126:129], v[146:149], v[184:187], v[126:129]
	v_mfma_f32_16x16x32_bf16 v[118:121], v[160:163], v[184:187], v[118:121]
	v_mfma_f32_16x16x32_bf16 v[110:113], v[146:149], v[192:195], v[110:113]
	v_mfma_f32_16x16x32_bf16 v[102:105], v[160:163], v[192:195], v[102:105]
	v_mfma_f32_16x16x32_bf16 v[94:97], v[146:149], v[206:209], v[94:97]
	v_mfma_f32_16x16x32_bf16 v[86:89], v[160:163], v[206:209], v[86:89]
	v_mfma_f32_16x16x32_bf16 v[78:81], v[146:149], v[214:217], v[78:81]
	v_mfma_f32_16x16x32_bf16 v[70:73], v[160:163], v[214:217], v[70:73]
	s_setprio 0
	s_setprio 1
	v_mfma_f32_16x16x32_bf16 v[122:125], v[164:167], v[180:183], v[122:125]
	v_mfma_f32_16x16x32_bf16 v[114:117], v[172:175], v[180:183], v[114:117]
	v_mfma_f32_16x16x32_bf16 v[106:109], v[164:167], v[188:191], v[106:109]
	v_mfma_f32_16x16x32_bf16 v[98:101], v[172:175], v[188:191], v[98:101]
	v_mfma_f32_16x16x32_bf16 v[90:93], v[164:167], v[202:205], v[90:93]
	v_mfma_f32_16x16x32_bf16 v[82:85], v[172:175], v[202:205], v[82:85]
	v_mfma_f32_16x16x32_bf16 v[74:77], v[164:167], v[210:213], v[74:77]
	v_mfma_f32_16x16x32_bf16 v[66:69], v[172:175], v[210:213], v[66:69]
	v_mfma_f32_16x16x32_bf16 v[122:125], v[168:171], v[184:187], v[122:125]
	v_mfma_f32_16x16x32_bf16 v[114:117], v[176:179], v[184:187], v[114:117]
	v_mfma_f32_16x16x32_bf16 v[106:109], v[168:171], v[192:195], v[106:109]
	v_mfma_f32_16x16x32_bf16 v[98:101], v[176:179], v[192:195], v[98:101]
	v_mfma_f32_16x16x32_bf16 v[90:93], v[168:171], v[206:209], v[90:93]
	v_mfma_f32_16x16x32_bf16 v[82:85], v[176:179], v[206:209], v[82:85]
	v_mfma_f32_16x16x32_bf16 v[74:77], v[168:171], v[214:217], v[74:77]
	v_mfma_f32_16x16x32_bf16 v[66:69], v[176:179], v[214:217], v[66:69]
	s_setprio 0
	s_barrier
; #define PG8_STAGE(bufoff, gbase, voff) do { _Pragma("unroll") for (int _i = 0; _i < 2; ++_i) \
;         __builtin_amdgcn_global_load_lds((const unsigned*)((const char*)(gbase) + (voff)[_i]), (PG8_LAS unsigned*)(lds + (bufoff) + ldsw + _i * 8192), 16, 0, 0); } while (0)
; #define PG8_LDA(dst, b, h) do { _Pragma("unroll") for (int m = 0; m < 4; ++m) _Pragma("unroll") for (int k = 0; k < 2; ++k) dst[m][k] = *(const PG8_LAS bf16x8*)(lds + PG8_SA(b, h) + aoff + m * 2048 + k * 1024); } while (0)
; #define PG8_LDB(dst, b, h) do { _Pragma("unroll") for (int n = 0; n < 2; ++n) _Pragma("unroll") for (int k = 0; k < 2; ++k) dst[n][k] = *(const PG8_LAS bf16x8*)(lds + PG8_SB(b, h) + boff + n * 2048 + k * 1024); } while (0)
; #define PG8_MMA(ai, bj, At, Bt) do { __builtin_amdgcn_s_setprio(1); _Pragma("unroll") for (int m = 0; m < 4; ++m) _Pragma("unroll") for (int n = 0; n < 2; ++n) _Pragma("unroll") for (int k = 0; k < 2; ++k) \
;         acc[ai][bj][m][n] = __builtin_amdgcn_mfma_f32_16x16x32_bf16(Bt[n][k], At[m][k], acc[ai][bj][m][n], 0, 0, 0); __builtin_amdgcn_s_setprio(0); } while (0)
; #define PG8_WAIT_V(n) asm volatile("s_waitcnt vmcnt(" #n ")" ::: "memory")
; #define PG8_WAIT_L(n) asm volatile("s_waitcnt lgkmcnt(" #n ")" ::: "memory")
; #define PG8_BAR __builtin_amdgcn_s_barrier()
; #define PG8_SCHED __builtin_amdgcn_sched_barrier(0)
; template <class Epi, class Sched>
; __device__ __forceinline__ void gemm_phase(PG8_LAS unsigned char* lds, const Gemm g, const Sched& S, const Epi& E) {
;     ...
;             PG8_LDB(B0, 1, 0); PG8_LDB(B1, 1, 1); PG8_SCHED; PG8_LDA(At, 1, 0); PG8_STAGE(PG8_SA(0, 1), a2 + hstep, voffA);
;             PG8_WAIT_V(8); PG8_WAIT_L(0); PG8_BAR; PG8_MMA(0, 0, At, B0); PG8_MMA(0, 1, At, B1); PG8_BAR; PG8_SCHED;
;             PG8_LDA(At, 1, 1); PG8_STAGE(PG8_SB(1, 0), b3, voffB); PG8_STAGE(PG8_SB(1, 1), b3 + hstep, voffB); PG8_STAGE(PG8_SA(1, 0), a3, voffA);
;             PG8_WAIT_V(8); PG8_WAIT_L(0); PG8_BAR; PG8_MMA(1, 0, At, B0); PG8_MMA(1, 1, At, B1); PG8_BAR; PG8_SCHED;
;         }
	s_add_i32 s34, s34, s3
	v_lshl_add_u64 v[154:155], v[154:155], 0, s[0:1]
	s_mov_b32 m0, s34
	ds_read_b128 v[180:183], v158 offset:49152
	ds_read_b128 v[184:187], v158 offset:50176
	ds_read_b128 v[188:191], v158 offset:51200
	ds_read_b128 v[192:195], v158 offset:52224
	ds_read_b128 v[202:205], v158 offset:53248
	ds_read_b128 v[206:209], v158 offset:54272
	ds_read_b128 v[210:213], v158 offset:55296
	ds_read_b128 v[214:217], v158 offset:56320
	global_load_lds_dwordx4 v[154:155], off
	v_lshl_add_u64 v[154:155], v[196:197], 0, s[0:1]
	s_add_i32 m0, s34, 0x2000
	s_add_i32 s34, s56, s3
	global_load_lds_dwordx4 v[154:155], off
	v_lshl_add_u64 v[154:155], v[218:219], 0, s[0:1]
	s_mov_b32 m0, s34
	s_nop 0
	global_load_lds_dwordx4 v[154:155], off
	v_lshl_add_u64 v[154:155], v[220:221], 0, s[0:1]
	s_add_i32 m0, s34, 0x2000
	s_nop 0
	global_load_lds_dwordx4 v[154:155], off
	v_lshl_add_u64 v[154:155], v[222:223], 0, s[0:1]
	s_mov_b32 m0, s37
	s_nop 0
	global_load_lds_dwordx4 v[154:155], off
	v_lshl_add_u64 v[154:155], v[224:225], 0, s[0:1]
	s_mov_b32 m0, s38
	s_nop 0
	global_load_lds_dwordx4 v[154:155], off
	s_waitcnt vmcnt(8)
	s_waitcnt lgkmcnt(0)
	s_barrier
	s_setprio 1
	s_waitcnt lgkmcnt(0)
	v_mfma_f32_16x16x32_bf16 v[62:65], v[130:133], v[180:183], v[62:65]
	v_mfma_f32_16x16x32_bf16 v[54:57], v[150:153], v[180:183], v[54:57]
	v_mfma_f32_16x16x32_bf16 v[46:49], v[130:133], v[188:191], v[46:49]
	v_mfma_f32_16x16x32_bf16 v[38:41], v[150:153], v[188:191], v[38:41]
	v_mfma_f32_16x16x32_bf16 v[30:33], v[130:133], v[202:205], v[30:33]
	v_mfma_f32_16x16x32_bf16 v[22:25], v[150:153], v[202:205], v[22:25]
	v_mfma_f32_16x16x32_bf16 v[14:17], v[130:133], v[210:213], v[14:17]
	v_mfma_f32_16x16x32_bf16 v[6:9], v[150:153], v[210:213], v[6:9]
	v_mfma_f32_16x16x32_bf16 v[62:65], v[146:149], v[184:187], v[62:65]
	v_mfma_f32_16x16x32_bf16 v[54:57], v[160:163], v[184:187], v[54:57]
	v_mfma_f32_16x16x32_bf16 v[46:49], v[146:149], v[192:195], v[46:49]
	v_mfma_f32_16x16x32_bf16 v[38:41], v[160:163], v[192:195], v[38:41]
	v_mfma_f32_16x16x32_bf16 v[30:33], v[146:149], v[206:209], v[30:33]
	v_mfma_f32_16x16x32_bf16 v[22:25], v[160:163], v[206:209], v[22:25]
	v_mfma_f32_16x16x32_bf16 v[14:17], v[146:149], v[214:217], v[14:17]
	v_mfma_f32_16x16x32_bf16 v[6:9], v[160:163], v[214:217], v[6:9]
	s_setprio 0
	s_setprio 1
	v_mfma_f32_16x16x32_bf16 v[58:61], v[164:167], v[180:183], v[58:61]
	v_mfma_f32_16x16x32_bf16 v[50:53], v[172:175], v[180:183], v[50:53]
	v_mfma_f32_16x16x32_bf16 v[42:45], v[164:167], v[188:191], v[42:45]
	v_mfma_f32_16x16x32_bf16 v[34:37], v[172:175], v[188:191], v[34:37]
	v_mfma_f32_16x16x32_bf16 v[26:29], v[164:167], v[202:205], v[26:29]
	v_mfma_f32_16x16x32_bf16 v[18:21], v[172:175], v[202:205], v[18:21]
	v_mfma_f32_16x16x32_bf16 v[10:13], v[164:167], v[210:213], v[10:13]
	v_mfma_f32_16x16x32_bf16 v[2:5], v[172:175], v[210:213], v[2:5]
	v_mfma_f32_16x16x32_bf16 v[58:61], v[168:171], v[184:187], v[58:61]
	v_mfma_f32_16x16x32_bf16 v[50:53], v[176:179], v[184:187], v[50:53]
	v_mfma_f32_16x16x32_bf16 v[42:45], v[168:171], v[192:195], v[42:45]
	v_mfma_f32_16x16x32_bf16 v[34:37], v[176:179], v[192:195], v[34:37]
	v_mfma_f32_16x16x32_bf16 v[26:29], v[168:171], v[206:209], v[26:29]
	v_mfma_f32_16x16x32_bf16 v[18:21], v[176:179], v[206:209], v[18:21]
	v_mfma_f32_16x16x32_bf16 v[10:13], v[168:171], v[214:217], v[10:13]
	v_mfma_f32_16x16x32_bf16 v[2:5], v[176:179], v[214:217], v[2:5]
	s_setprio 0
	s_barrier
	s_add_u32 s42, s42, 0x100
	s_addc_u32 s43, s43, 0
	s_add_u32 s14, s14, 0x100
	s_addc_u32 s15, s15, 0
	s_cmp_ge_u32 s55, s33
	s_mov_b32 s34, s55
